# v024 + no s_setprio in the gate/up GEMM K-loop MFMA segments
# baseline (speedup 1.0000x reference)
.LBB0_1248:
	s_add_u32 s22, s20, 0xfffc0080
	s_addc_u32 s23, s21, -1
	s_add_i32 s48, 0, 0x10000
	s_cmp_eq_u32 s47, 12
	s_cselect_b32 s25, s13, s23
	s_cselect_b32 s24, s19, s22
	s_cselect_b32 s23, s11, s46
	s_cselect_b32 s22, s44, s45
	s_add_i32 s50, 0, 0x14000
	v_add_u32_e32 v142, s48, v171
	v_add_u32_e32 v164, s50, v171
	ds_read_b128 v[130:133], v142
	ds_read_b128 v[134:137], v142 offset:1024
	ds_read_b128 v[138:141], v142 offset:2048
	ds_read_b128 v[142:145], v142 offset:3072
	ds_read_b128 v[160:163], v164
	ds_read_b128 v[176:179], v164 offset:1024
	ds_read_b128 v[180:183], v164 offset:2048
	ds_read_b128 v[184:187], v164 offset:3072
	v_lshl_add_u64 v[164:165], s[20:21], 0, v[156:157]
	s_add_i32 m0, s31, 0xc000
	ds_read_b128 v[188:191], v175
	ds_read_b128 v[192:195], v175 offset:1024
	ds_read_b128 v[196:199], v175 offset:2048
	ds_read_b128 v[200:203], v175 offset:3072
	ds_read_b128 v[204:207], v175 offset:4096
	ds_read_b128 v[208:211], v175 offset:5120
	ds_read_b128 v[212:215], v175 offset:6144
	ds_read_b128 v[216:219], v175 offset:7168
	global_load_lds_dwordx4 v[164:165], off
	v_lshl_add_u64 v[164:165], s[20:21], 0, v[158:159]
	s_add_i32 m0, s31, 0xe000
	s_nop 0
	global_load_lds_dwordx4 v[164:165], off
	s_waitcnt vmcnt(8)
	s_waitcnt lgkmcnt(0)
	s_barrier
	s_waitcnt lgkmcnt(0)
	v_mfma_f32_16x16x32_bf16 v[126:129], v[130:133], v[188:191], v[126:129]
	v_mfma_f32_16x16x32_bf16 v[122:125], v[138:141], v[188:191], v[122:125]
	v_mfma_f32_16x16x32_bf16 v[110:113], v[130:133], v[196:199], v[110:113]
	v_mfma_f32_16x16x32_bf16 v[106:109], v[138:141], v[196:199], v[106:109]
	v_mfma_f32_16x16x32_bf16 v[94:97], v[130:133], v[204:207], v[94:97]
	v_mfma_f32_16x16x32_bf16 v[90:93], v[138:141], v[204:207], v[90:93]
	v_mfma_f32_16x16x32_bf16 v[78:81], v[130:133], v[212:215], v[78:81]
	v_mfma_f32_16x16x32_bf16 v[74:77], v[138:141], v[212:215], v[74:77]
	v_mfma_f32_16x16x32_bf16 v[126:129], v[134:137], v[192:195], v[126:129]
	v_mfma_f32_16x16x32_bf16 v[122:125], v[142:145], v[192:195], v[122:125]
	v_mfma_f32_16x16x32_bf16 v[110:113], v[134:137], v[200:203], v[110:113]
	v_mfma_f32_16x16x32_bf16 v[106:109], v[142:145], v[200:203], v[106:109]
	v_mfma_f32_16x16x32_bf16 v[94:97], v[134:137], v[208:211], v[94:97]
	v_mfma_f32_16x16x32_bf16 v[90:93], v[142:145], v[208:211], v[90:93]
	v_mfma_f32_16x16x32_bf16 v[78:81], v[134:137], v[216:219], v[78:81]
	v_mfma_f32_16x16x32_bf16 v[74:77], v[142:145], v[216:219], v[74:77]
	v_mfma_f32_16x16x32_bf16 v[118:121], v[160:163], v[188:191], v[118:121]
	v_mfma_f32_16x16x32_bf16 v[114:117], v[180:183], v[188:191], v[114:117]
	v_mfma_f32_16x16x32_bf16 v[102:105], v[160:163], v[196:199], v[102:105]
	v_mfma_f32_16x16x32_bf16 v[98:101], v[180:183], v[196:199], v[98:101]
	v_mfma_f32_16x16x32_bf16 v[86:89], v[160:163], v[204:207], v[86:89]
	v_mfma_f32_16x16x32_bf16 v[82:85], v[180:183], v[204:207], v[82:85]
	v_mfma_f32_16x16x32_bf16 v[70:73], v[160:163], v[212:215], v[70:73]
	v_mfma_f32_16x16x32_bf16 v[66:69], v[180:183], v[212:215], v[66:69]
	v_mfma_f32_16x16x32_bf16 v[118:121], v[176:179], v[192:195], v[118:121]
	v_mfma_f32_16x16x32_bf16 v[114:117], v[184:187], v[192:195], v[114:117]
	v_mfma_f32_16x16x32_bf16 v[102:105], v[176:179], v[200:203], v[102:105]
	v_mfma_f32_16x16x32_bf16 v[98:101], v[184:187], v[200:203], v[98:101]
	v_mfma_f32_16x16x32_bf16 v[86:89], v[176:179], v[208:211], v[86:89]
	v_mfma_f32_16x16x32_bf16 v[82:85], v[184:187], v[208:211], v[82:85]
	v_mfma_f32_16x16x32_bf16 v[70:73], v[176:179], v[216:219], v[70:73]
	v_mfma_f32_16x16x32_bf16 v[66:69], v[184:187], v[216:219], v[66:69]
	s_barrier
	s_add_i32 s48, s48, s30
	v_lshl_add_u64 v[164:165], s[22:23], 0, v[0:1]
	s_mov_b32 m0, s48
	ds_read_b128 v[188:191], v175 offset:16384
	ds_read_b128 v[192:195], v175 offset:17408
	ds_read_b128 v[196:199], v175 offset:18432
	ds_read_b128 v[200:203], v175 offset:19456
	ds_read_b128 v[204:207], v175 offset:20480
	ds_read_b128 v[208:211], v175 offset:21504
	ds_read_b128 v[212:215], v175 offset:22528
	ds_read_b128 v[216:219], v175 offset:23552
	global_load_lds_dwordx4 v[164:165], off
	s_add_i32 m0, s48, 0x2000
	s_add_u32 s48, s22, 0x40000
	v_lshl_add_u64 v[168:169], s[22:23], 0, v[146:147]
	s_addc_u32 s49, s23, 0
	s_add_i32 s50, s50, s30
	global_load_lds_dwordx4 v[168:169], off
	v_lshl_add_u64 v[172:173], s[48:49], 0, v[0:1]
	s_mov_b32 m0, s50
	v_lshl_add_u64 v[220:221], s[24:25], 0, v[148:149]
	global_load_lds_dwordx4 v[172:173], off
	v_lshl_add_u64 v[172:173], s[48:49], 0, v[146:147]
	s_add_i32 m0, s50, 0x2000
	s_nop 0
	global_load_lds_dwordx4 v[172:173], off
	v_lshl_add_u64 v[172:173], s[24:25], 0, v[150:151]
	s_mov_b32 m0, s31
	s_nop 0
	global_load_lds_dwordx4 v[172:173], off
	s_mov_b32 m0, s33
	s_nop 0
	global_load_lds_dwordx4 v[220:221], off
	s_waitcnt vmcnt(8)
	s_waitcnt lgkmcnt(0)
	s_barrier
	s_waitcnt lgkmcnt(0)
	v_mfma_f32_16x16x32_bf16 v[62:65], v[130:133], v[188:191], v[62:65]
	v_mfma_f32_16x16x32_bf16 v[58:61], v[138:141], v[188:191], v[58:61]
	v_mfma_f32_16x16x32_bf16 v[46:49], v[130:133], v[196:199], v[46:49]
	v_mfma_f32_16x16x32_bf16 v[42:45], v[138:141], v[196:199], v[42:45]
	v_mfma_f32_16x16x32_bf16 v[30:33], v[130:133], v[204:207], v[30:33]
	v_mfma_f32_16x16x32_bf16 v[26:29], v[138:141], v[204:207], v[26:29]
	v_mfma_f32_16x16x32_bf16 v[14:17], v[130:133], v[212:215], v[14:17]
	v_mfma_f32_16x16x32_bf16 v[10:13], v[138:141], v[212:215], v[10:13]
	v_mfma_f32_16x16x32_bf16 v[62:65], v[134:137], v[192:195], v[62:65]
	v_mfma_f32_16x16x32_bf16 v[58:61], v[142:145], v[192:195], v[58:61]
	v_mfma_f32_16x16x32_bf16 v[46:49], v[134:137], v[200:203], v[46:49]
	v_mfma_f32_16x16x32_bf16 v[42:45], v[142:145], v[200:203], v[42:45]
	v_mfma_f32_16x16x32_bf16 v[30:33], v[134:137], v[208:211], v[30:33]
	v_mfma_f32_16x16x32_bf16 v[26:29], v[142:145], v[208:211], v[26:29]
	v_mfma_f32_16x16x32_bf16 v[14:17], v[134:137], v[216:219], v[14:17]
	v_mfma_f32_16x16x32_bf16 v[10:13], v[142:145], v[216:219], v[10:13]
	v_mfma_f32_16x16x32_bf16 v[54:57], v[160:163], v[188:191], v[54:57]
	v_mfma_f32_16x16x32_bf16 v[50:53], v[180:183], v[188:191], v[50:53]
	v_mfma_f32_16x16x32_bf16 v[38:41], v[160:163], v[196:199], v[38:41]
	v_mfma_f32_16x16x32_bf16 v[34:37], v[180:183], v[196:199], v[34:37]
	v_mfma_f32_16x16x32_bf16 v[22:25], v[160:163], v[204:207], v[22:25]
	v_mfma_f32_16x16x32_bf16 v[18:21], v[180:183], v[204:207], v[18:21]
	v_mfma_f32_16x16x32_bf16 v[6:9], v[160:163], v[212:215], v[6:9]
	v_mfma_f32_16x16x32_bf16 v[2:5], v[180:183], v[212:215], v[2:5]
	v_mfma_f32_16x16x32_bf16 v[54:57], v[176:179], v[192:195], v[54:57]
	v_mfma_f32_16x16x32_bf16 v[50:53], v[184:187], v[192:195], v[50:53]
	v_mfma_f32_16x16x32_bf16 v[38:41], v[176:179], v[200:203], v[38:41]
	v_mfma_f32_16x16x32_bf16 v[34:37], v[184:187], v[200:203], v[34:37]
	v_mfma_f32_16x16x32_bf16 v[22:25], v[176:179], v[208:211], v[22:25]
	v_mfma_f32_16x16x32_bf16 v[18:21], v[184:187], v[208:211], v[18:21]
	v_mfma_f32_16x16x32_bf16 v[6:9], v[176:179], v[216:219], v[6:9]
	v_mfma_f32_16x16x32_bf16 v[2:5], v[184:187], v[216:219], v[2:5]
	s_barrier
	s_add_i32 s48, 0, 0x18000
	s_add_i32 s49, 0, 0x1c000
	v_add_u32_e32 v142, s48, v171
	v_add_u32_e32 v166, s49, v171
	ds_read_b128 v[130:133], v142
	ds_read_b128 v[134:137], v142 offset:1024
	ds_read_b128 v[138:141], v142 offset:2048
	ds_read_b128 v[142:145], v142 offset:3072
	ds_read_b128 v[160:163], v166
	ds_read_b128 v[176:179], v166 offset:1024
	ds_read_b128 v[180:183], v166 offset:2048
	ds_read_b128 v[184:187], v166 offset:3072
	s_add_u32 s24, s24, 0x40000
	s_addc_u32 s25, s25, 0
	s_mov_b32 m0, s34
	v_lshl_add_u64 v[222:223], s[24:25], 0, v[150:151]
	ds_read_b128 v[188:191], v175 offset:32768
	ds_read_b128 v[192:195], v175 offset:33792
	ds_read_b128 v[196:199], v175 offset:34816
	ds_read_b128 v[200:203], v175 offset:35840
	ds_read_b128 v[204:207], v175 offset:36864
	ds_read_b128 v[208:211], v175 offset:37888
	ds_read_b128 v[212:215], v175 offset:38912
	ds_read_b128 v[216:219], v175 offset:39936
	global_load_lds_dwordx4 v[222:223], off
	v_lshl_add_u64 v[222:223], s[24:25], 0, v[148:149]
	s_mov_b32 m0, s35
	s_nop 0
	global_load_lds_dwordx4 v[222:223], off
	s_waitcnt vmcnt(8)
	s_waitcnt lgkmcnt(0)
	s_barrier
	s_waitcnt lgkmcnt(0)
	v_mfma_f32_16x16x32_bf16 v[126:129], v[130:133], v[188:191], v[126:129]
	v_mfma_f32_16x16x32_bf16 v[122:125], v[138:141], v[188:191], v[122:125]
	v_mfma_f32_16x16x32_bf16 v[110:113], v[130:133], v[196:199], v[110:113]
	v_mfma_f32_16x16x32_bf16 v[106:109], v[138:141], v[196:199], v[106:109]
	v_mfma_f32_16x16x32_bf16 v[94:97], v[130:133], v[204:207], v[94:97]
	v_mfma_f32_16x16x32_bf16 v[90:93], v[138:141], v[204:207], v[90:93]
	v_mfma_f32_16x16x32_bf16 v[78:81], v[130:133], v[212:215], v[78:81]
	v_mfma_f32_16x16x32_bf16 v[74:77], v[138:141], v[212:215], v[74:77]
	v_mfma_f32_16x16x32_bf16 v[126:129], v[134:137], v[192:195], v[126:129]
	v_mfma_f32_16x16x32_bf16 v[122:125], v[142:145], v[192:195], v[122:125]
	v_mfma_f32_16x16x32_bf16 v[110:113], v[134:137], v[200:203], v[110:113]
	v_mfma_f32_16x16x32_bf16 v[106:109], v[142:145], v[200:203], v[106:109]
	v_mfma_f32_16x16x32_bf16 v[94:97], v[134:137], v[208:211], v[94:97]
	v_mfma_f32_16x16x32_bf16 v[90:93], v[142:145], v[208:211], v[90:93]
	v_mfma_f32_16x16x32_bf16 v[78:81], v[134:137], v[216:219], v[78:81]
	v_mfma_f32_16x16x32_bf16 v[74:77], v[142:145], v[216:219], v[74:77]
	v_mfma_f32_16x16x32_bf16 v[118:121], v[160:163], v[188:191], v[118:121]
	v_mfma_f32_16x16x32_bf16 v[114:117], v[180:183], v[188:191], v[114:117]
	v_mfma_f32_16x16x32_bf16 v[102:105], v[160:163], v[196:199], v[102:105]
	v_mfma_f32_16x16x32_bf16 v[98:101], v[180:183], v[196:199], v[98:101]
	v_mfma_f32_16x16x32_bf16 v[86:89], v[160:163], v[204:207], v[86:89]
	v_mfma_f32_16x16x32_bf16 v[82:85], v[180:183], v[204:207], v[82:85]
	v_mfma_f32_16x16x32_bf16 v[70:73], v[160:163], v[212:215], v[70:73]
	v_mfma_f32_16x16x32_bf16 v[66:69], v[180:183], v[212:215], v[66:69]
	v_mfma_f32_16x16x32_bf16 v[118:121], v[176:179], v[192:195], v[118:121]
	v_mfma_f32_16x16x32_bf16 v[114:117], v[184:187], v[192:195], v[114:117]
	v_mfma_f32_16x16x32_bf16 v[102:105], v[176:179], v[200:203], v[102:105]
	v_mfma_f32_16x16x32_bf16 v[98:101], v[184:187], v[200:203], v[98:101]
	v_mfma_f32_16x16x32_bf16 v[86:89], v[176:179], v[208:211], v[86:89]
	v_mfma_f32_16x16x32_bf16 v[82:85], v[184:187], v[208:211], v[82:85]
	v_mfma_f32_16x16x32_bf16 v[70:73], v[176:179], v[216:219], v[70:73]
	v_mfma_f32_16x16x32_bf16 v[66:69], v[184:187], v[216:219], v[66:69]
	s_barrier
	s_add_i32 s24, s48, s30
	v_lshl_add_u64 v[164:165], v[164:165], 0, s[80:81]
	s_mov_b32 m0, s24
	ds_read_b128 v[188:191], v175 offset:49152
	ds_read_b128 v[192:195], v175 offset:50176
	ds_read_b128 v[196:199], v175 offset:51200
	ds_read_b128 v[200:203], v175 offset:52224
	ds_read_b128 v[204:207], v175 offset:53248
	ds_read_b128 v[208:211], v175 offset:54272
	ds_read_b128 v[212:215], v175 offset:55296
	ds_read_b128 v[216:219], v175 offset:56320
	global_load_lds_dwordx4 v[164:165], off
	s_add_i32 m0, s24, 0x2000
	s_add_u32 s22, s22, 0x40080
	v_lshl_add_u64 v[164:165], v[168:169], 0, s[80:81]
	s_addc_u32 s23, s23, 0
	s_add_i32 s24, s49, s30
	global_load_lds_dwordx4 v[164:165], off
	v_lshl_add_u64 v[164:165], s[22:23], 0, v[0:1]
	s_mov_b32 m0, s24
	s_nop 0
	global_load_lds_dwordx4 v[164:165], off
	v_lshl_add_u64 v[164:165], s[22:23], 0, v[146:147]
	s_add_i32 m0, s24, 0x2000
	s_nop 0
	global_load_lds_dwordx4 v[164:165], off
	v_lshl_add_u64 v[164:165], v[172:173], 0, s[80:81]
	s_mov_b32 m0, s41
	s_nop 0
	global_load_lds_dwordx4 v[164:165], off
	v_lshl_add_u64 v[164:165], v[220:221], 0, s[80:81]
	s_mov_b32 m0, s42
	s_nop 0
	global_load_lds_dwordx4 v[164:165], off
	s_waitcnt vmcnt(8)
	s_waitcnt lgkmcnt(0)
	s_barrier
	s_waitcnt lgkmcnt(0)
	v_mfma_f32_16x16x32_bf16 v[62:65], v[130:133], v[188:191], v[62:65]
	v_mfma_f32_16x16x32_bf16 v[58:61], v[138:141], v[188:191], v[58:61]
	v_mfma_f32_16x16x32_bf16 v[46:49], v[130:133], v[196:199], v[46:49]
	v_mfma_f32_16x16x32_bf16 v[42:45], v[138:141], v[196:199], v[42:45]
	v_mfma_f32_16x16x32_bf16 v[30:33], v[130:133], v[204:207], v[30:33]
	v_mfma_f32_16x16x32_bf16 v[26:29], v[138:141], v[204:207], v[26:29]
	v_mfma_f32_16x16x32_bf16 v[14:17], v[130:133], v[212:215], v[14:17]
	v_mfma_f32_16x16x32_bf16 v[10:13], v[138:141], v[212:215], v[10:13]
	v_mfma_f32_16x16x32_bf16 v[62:65], v[134:137], v[192:195], v[62:65]
	v_mfma_f32_16x16x32_bf16 v[58:61], v[142:145], v[192:195], v[58:61]
	v_mfma_f32_16x16x32_bf16 v[46:49], v[134:137], v[200:203], v[46:49]
	v_mfma_f32_16x16x32_bf16 v[42:45], v[142:145], v[200:203], v[42:45]
	v_mfma_f32_16x16x32_bf16 v[30:33], v[134:137], v[208:211], v[30:33]
	v_mfma_f32_16x16x32_bf16 v[26:29], v[142:145], v[208:211], v[26:29]
	v_mfma_f32_16x16x32_bf16 v[14:17], v[134:137], v[216:219], v[14:17]
	v_mfma_f32_16x16x32_bf16 v[10:13], v[142:145], v[216:219], v[10:13]
	v_mfma_f32_16x16x32_bf16 v[54:57], v[160:163], v[188:191], v[54:57]
	v_mfma_f32_16x16x32_bf16 v[50:53], v[180:183], v[188:191], v[50:53]
	v_mfma_f32_16x16x32_bf16 v[38:41], v[160:163], v[196:199], v[38:41]
	v_mfma_f32_16x16x32_bf16 v[34:37], v[180:183], v[196:199], v[34:37]
	v_mfma_f32_16x16x32_bf16 v[22:25], v[160:163], v[204:207], v[22:25]
	v_mfma_f32_16x16x32_bf16 v[18:21], v[180:183], v[204:207], v[18:21]
	v_mfma_f32_16x16x32_bf16 v[6:9], v[160:163], v[212:215], v[6:9]
	v_mfma_f32_16x16x32_bf16 v[2:5], v[180:183], v[212:215], v[2:5]
	v_mfma_f32_16x16x32_bf16 v[54:57], v[176:179], v[192:195], v[54:57]
	v_mfma_f32_16x16x32_bf16 v[50:53], v[184:187], v[192:195], v[50:53]
	v_mfma_f32_16x16x32_bf16 v[38:41], v[176:179], v[200:203], v[38:41]
	v_mfma_f32_16x16x32_bf16 v[34:37], v[184:187], v[200:203], v[34:37]
	v_mfma_f32_16x16x32_bf16 v[22:25], v[176:179], v[208:211], v[22:25]
	v_mfma_f32_16x16x32_bf16 v[18:21], v[184:187], v[208:211], v[18:21]
	v_mfma_f32_16x16x32_bf16 v[6:9], v[176:179], v[216:219], v[6:9]
	v_mfma_f32_16x16x32_bf16 v[2:5], v[184:187], v[216:219], v[2:5]
	s_barrier
	s_add_i32 s47, s47, 2
	s_add_u32 s20, s20, 0x100
	s_addc_u32 s21, s21, 0
	s_add_u32 s45, s45, 0x100
	s_addc_u32 s46, s46, 0
	s_cmp_gt_u32 s47, 13
	s_cbranch_scc0 .LBB0_1248
	s_and_b64 vcc, exec, s[6:7]
	s_cbranch_vccz .LBB0_1251
	s_barrier
